# phase-0 rmsnorm rows loop hand-written with next-row prefetch (double-buffered registers, scalar addressing)
# baseline (speedup 1.0000x reference)
.LBB0_107:
	v_and_b32_e32 v1, 0xfc, v162
	v_mov_b32_e32 v19, 0
	s_mov_b32 s0, 0x10200
	v_lshlrev_b32_e32 v158, 2, v1
	v_cmp_gt_i32_e64 s[2:3], s0, v152
	s_mov_b64 s[0:1], exec
	s_nop 0
	v_writelane_b32 v252, s2, 24
	s_nop 1
	v_writelane_b32 v252, s3, 25
	s_and_b64 s[2:3], s[0:1], s[2:3]
	s_mov_b64 exec, s[2:3]
	s_cbranch_execz .LBB0_112
	v_readlane_b32 s22, v252, 4
	v_readlane_b32 s23, v252, 5
	v_readlane_b32 s12, v253, 0
	v_readlane_b32 s13, v253, 1
	v_readlane_b32 s14, v253, 2
	v_readlane_b32 s15, v253, 3
	v_readfirstlane_b32 s16, v152
	s_nop 4
	global_load_dwordx4 v[2:5], v158, s[22:23]
	global_load_dwordx4 v[6:9], v158, s[22:23] offset:1024
	global_load_dwordx4 v[10:13], v158, s[22:23] offset:2048
	global_load_dwordx4 v[14:17], v158, s[22:23] offset:3072
	v_mov_b32_e32 v159, v19
	v_mov_b32_e32 v1, 0x358637bd
	v_mov_b32_e32 v59, 0x3a800000
	v_lshrrev_b32_e32 v20, 1, v158
	s_sub_u32 s17, s16, 0x10000
	s_cmp_gt_u32 s16, 0xffff
	s_cselect_b32 s17, s17, s16
	s_cselect_b32 s18, s14, s12
	s_cselect_b32 s19, s15, s13
	s_lshr_b32 s20, s17, 20
	s_lshl_b32 s17, s17, 12
	s_add_u32 s18, s18, s17
	s_addc_u32 s19, s19, s20
	global_load_dwordx4 v[22:25], v158, s[18:19]
	global_load_dwordx4 v[26:29], v158, s[18:19] offset:1024
	global_load_dwordx4 v[30:33], v158, s[18:19] offset:2048
	global_load_dwordx4 v[34:37], v158, s[18:19] offset:3072
.Lrms0_loop:
	s_add_u32 s21, s16, s6
	s_cmp_lt_u32 s21, 0x10200
	s_cbranch_scc0 .Lrms0_skip_a
	s_sub_u32 s17, s21, 0x10000
	s_cmp_gt_u32 s21, 0xffff
	s_cselect_b32 s17, s17, s21
	s_cselect_b32 s18, s14, s12
	s_cselect_b32 s19, s15, s13
	s_lshr_b32 s20, s17, 20
	s_lshl_b32 s17, s17, 12
	s_add_u32 s18, s18, s17
	s_addc_u32 s19, s19, s20
	global_load_dwordx4 v[38:41], v158, s[18:19]
	global_load_dwordx4 v[42:45], v158, s[18:19] offset:1024
	global_load_dwordx4 v[46:49], v158, s[18:19] offset:2048
	global_load_dwordx4 v[50:53], v158, s[18:19] offset:3072
	s_waitcnt vmcnt(4)
	s_branch .Lrms0_comp_a
.Lrms0_skip_a:
	s_waitcnt vmcnt(0)
.Lrms0_comp_a:
	v_pk_mul_f32 v[54:55], v[22:23], v[22:23]
	v_pk_mul_f32 v[56:57], v[24:25], v[24:25]
	v_pk_fma_f32 v[54:55], v[26:27], v[26:27], v[54:55]
	v_pk_fma_f32 v[56:57], v[28:29], v[28:29], v[56:57]
	v_pk_fma_f32 v[54:55], v[30:31], v[30:31], v[54:55]
	v_pk_fma_f32 v[56:57], v[32:33], v[32:33], v[56:57]
	v_pk_fma_f32 v[54:55], v[34:35], v[34:35], v[54:55]
	v_pk_fma_f32 v[56:57], v[36:37], v[36:37], v[56:57]
	s_nop 0
	v_pk_add_f32 v[54:55], v[54:55], v[56:57]
	s_nop 0
	v_add_f32_e32 v21, v54, v55
	s_nop 1
	v_add_f32_dpp v21, v21, v21 quad_perm:[1,0,3,2] row_mask:0xf bank_mask:0xf bound_ctrl:1
	s_nop 1
	v_add_f32_dpp v21, v21, v21 quad_perm:[2,3,0,1] row_mask:0xf bank_mask:0xf bound_ctrl:1
	s_nop 1
	v_add_f32_dpp v21, v21, v21 row_half_mirror row_mask:0xf bank_mask:0xf bound_ctrl:1
	s_nop 1
	v_add_f32_dpp v21, v21, v21 row_mirror row_mask:0xf bank_mask:0xf bound_ctrl:1
	s_nop 1
	v_mov_b32_dpp v18, v21 row_bcast:15 row_mask:0xa bank_mask:0xf
	v_add_f32_e32 v18, v21, v18
	s_nop 1
	v_mov_b32_dpp v58, v18 row_bcast:31 row_mask:0xc bank_mask:0xf
	v_add_f32_e32 v18, v18, v58
	s_nop 0
	v_readlane_b32 s4, v18, 63
	s_nop 1
	v_fma_f32 v18, s4, v59, v1
	v_rsq_f32_e32 v18, v18
	s_nop 0
	v_mul_f32_e32 v22, v22, v18
	v_mul_f32_e32 v23, v23, v18
	v_mul_f32_e32 v24, v24, v18
	v_mul_f32_e32 v25, v25, v18
	v_mul_f32_e32 v26, v26, v18
	v_mul_f32_e32 v27, v27, v18
	v_mul_f32_e32 v28, v28, v18
	v_mul_f32_e32 v29, v29, v18
	v_mul_f32_e32 v30, v30, v18
	v_mul_f32_e32 v31, v31, v18
	v_mul_f32_e32 v32, v32, v18
	v_mul_f32_e32 v33, v33, v18
	v_mul_f32_e32 v34, v34, v18
	v_mul_f32_e32 v35, v35, v18
	v_mul_f32_e32 v36, v36, v18
	v_mul_f32_e32 v37, v37, v18
	v_mul_f32_e32 v22, v2, v22
	v_mul_f32_e32 v23, v3, v23
	v_mul_f32_e32 v24, v4, v24
	v_mul_f32_e32 v25, v5, v25
	v_mul_f32_e32 v26, v6, v26
	v_mul_f32_e32 v27, v7, v27
	v_mul_f32_e32 v28, v8, v28
	v_mul_f32_e32 v29, v9, v29
	v_mul_f32_e32 v30, v10, v30
	v_mul_f32_e32 v31, v11, v31
	v_mul_f32_e32 v32, v12, v32
	v_mul_f32_e32 v33, v13, v33
	v_mul_f32_e32 v34, v14, v34
	v_mul_f32_e32 v35, v15, v35
	v_mul_f32_e32 v36, v16, v36
	v_mul_f32_e32 v37, v17, v37
	v_cvt_pk_bf16_f32 v22, v22, v23
	v_cvt_pk_bf16_f32 v23, v24, v25
	v_cvt_pk_bf16_f32 v24, v26, v27
	v_cvt_pk_bf16_f32 v25, v28, v29
	v_cvt_pk_bf16_f32 v26, v30, v31
	v_cvt_pk_bf16_f32 v27, v32, v33
	v_cvt_pk_bf16_f32 v28, v34, v35
	v_cvt_pk_bf16_f32 v29, v36, v37
	s_lshl_b32 s24, s16, 11
	s_lshr_b32 s25, s16, 21
	s_add_u32 s24, s94, s24
	s_addc_u32 s25, s95, s25
	global_store_dwordx2 v20, v[22:23], s[24:25]
	global_store_dwordx2 v20, v[24:25], s[24:25] offset:512
	global_store_dwordx2 v20, v[26:27], s[24:25] offset:1024
	global_store_dwordx2 v20, v[28:29], s[24:25] offset:1536
	s_mov_b32 s16, s21
	s_cmp_lt_u32 s16, 0x10200
	s_cbranch_scc0 .LBB0_112
	s_add_u32 s21, s16, s6
	s_cmp_lt_u32 s21, 0x10200
	s_cbranch_scc0 .Lrms0_skip_b
	s_sub_u32 s17, s21, 0x10000
	s_cmp_gt_u32 s21, 0xffff
	s_cselect_b32 s17, s17, s21
	s_cselect_b32 s18, s14, s12
	s_cselect_b32 s19, s15, s13
	s_lshr_b32 s20, s17, 20
	s_lshl_b32 s17, s17, 12
	s_add_u32 s18, s18, s17
	s_addc_u32 s19, s19, s20
	global_load_dwordx4 v[22:25], v158, s[18:19]
	global_load_dwordx4 v[26:29], v158, s[18:19] offset:1024
	global_load_dwordx4 v[30:33], v158, s[18:19] offset:2048
	global_load_dwordx4 v[34:37], v158, s[18:19] offset:3072
	s_waitcnt vmcnt(4)
	s_branch .Lrms0_comp_b

.Lrms0_comp_b:
	v_pk_mul_f32 v[54:55], v[38:39], v[38:39]
	v_pk_mul_f32 v[56:57], v[40:41], v[40:41]
	v_pk_fma_f32 v[54:55], v[42:43], v[42:43], v[54:55]
	v_pk_fma_f32 v[56:57], v[44:45], v[44:45], v[56:57]
	v_pk_fma_f32 v[54:55], v[46:47], v[46:47], v[54:55]
	v_pk_fma_f32 v[56:57], v[48:49], v[48:49], v[56:57]
	v_pk_fma_f32 v[54:55], v[50:51], v[50:51], v[54:55]
	v_pk_fma_f32 v[56:57], v[52:53], v[52:53], v[56:57]
	s_nop 0
	v_pk_add_f32 v[54:55], v[54:55], v[56:57]
	s_nop 0
	v_add_f32_e32 v21, v54, v55
	s_nop 1
	v_add_f32_dpp v21, v21, v21 quad_perm:[1,0,3,2] row_mask:0xf bank_mask:0xf bound_ctrl:1
	s_nop 1
	v_add_f32_dpp v21, v21, v21 quad_perm:[2,3,0,1] row_mask:0xf bank_mask:0xf bound_ctrl:1
	s_nop 1
	v_add_f32_dpp v21, v21, v21 row_half_mirror row_mask:0xf bank_mask:0xf bound_ctrl:1
	s_nop 1
	v_add_f32_dpp v21, v21, v21 row_mirror row_mask:0xf bank_mask:0xf bound_ctrl:1
	s_nop 1
	v_mov_b32_dpp v18, v21 row_bcast:15 row_mask:0xa bank_mask:0xf
	v_add_f32_e32 v18, v21, v18
	s_nop 1
	v_mov_b32_dpp v58, v18 row_bcast:31 row_mask:0xc bank_mask:0xf
	v_add_f32_e32 v18, v18, v58
	s_nop 0
	v_readlane_b32 s4, v18, 63
	s_nop 1
	v_fma_f32 v18, s4, v59, v1
	v_rsq_f32_e32 v18, v18
	s_nop 0
	v_mul_f32_e32 v38, v38, v18
	v_mul_f32_e32 v39, v39, v18
	v_mul_f32_e32 v40, v40, v18
	v_mul_f32_e32 v41, v41, v18
	v_mul_f32_e32 v42, v42, v18
	v_mul_f32_e32 v43, v43, v18
	v_mul_f32_e32 v44, v44, v18
	v_mul_f32_e32 v45, v45, v18
	v_mul_f32_e32 v46, v46, v18
	v_mul_f32_e32 v47, v47, v18
	v_mul_f32_e32 v48, v48, v18
	v_mul_f32_e32 v49, v49, v18
	v_mul_f32_e32 v50, v50, v18
	v_mul_f32_e32 v51, v51, v18
	v_mul_f32_e32 v52, v52, v18
	v_mul_f32_e32 v53, v53, v18
	v_mul_f32_e32 v38, v2, v38
	v_mul_f32_e32 v39, v3, v39
	v_mul_f32_e32 v40, v4, v40
	v_mul_f32_e32 v41, v5, v41
	v_mul_f32_e32 v42, v6, v42
	v_mul_f32_e32 v43, v7, v43
	v_mul_f32_e32 v44, v8, v44
	v_mul_f32_e32 v45, v9, v45
	v_mul_f32_e32 v46, v10, v46
	v_mul_f32_e32 v47, v11, v47
	v_mul_f32_e32 v48, v12, v48
	v_mul_f32_e32 v49, v13, v49
	v_mul_f32_e32 v50, v14, v50
	v_mul_f32_e32 v51, v15, v51
	v_mul_f32_e32 v52, v16, v52
	v_mul_f32_e32 v53, v17, v53
	v_cvt_pk_bf16_f32 v38, v38, v39
	v_cvt_pk_bf16_f32 v39, v40, v41
	v_cvt_pk_bf16_f32 v40, v42, v43
	v_cvt_pk_bf16_f32 v41, v44, v45
	v_cvt_pk_bf16_f32 v42, v46, v47
	v_cvt_pk_bf16_f32 v43, v48, v49
	v_cvt_pk_bf16_f32 v44, v50, v51
	v_cvt_pk_bf16_f32 v45, v52, v53
	s_lshl_b32 s24, s16, 11
	s_lshr_b32 s25, s16, 21
	s_add_u32 s24, s94, s24
	s_addc_u32 s25, s95, s25
	global_store_dwordx2 v20, v[38:39], s[24:25]
	global_store_dwordx2 v20, v[40:41], s[24:25] offset:512
	global_store_dwordx2 v20, v[42:43], s[24:25] offset:1024
	global_store_dwordx2 v20, v[44:45], s[24:25] offset:1536
	s_mov_b32 s16, s21
	s_cmp_lt_u32 s16, 0x10200
	s_cbranch_scc0 .LBB0_112
	s_branch .Lrms0_loop
